# v35 + neighbourhood-attention QK MFMAs in S0S0S1S1 order (refill reads and counted waits re-derived)
# baseline (speedup 1.0000x reference)
; #define A2_SETKC(SOFF) _Pragma("unroll") for (int _i = 0; _i < NKB; ++_i) kc[_i] = kbase[_i] + (unsigned)(SOFF)
; #define A2_SETVC(SOFF) _Pragma("unroll") for (int _i = 0; _i < 4; ++_i) vc[_i] = vbase[_i] + (unsigned)(SOFF)
; template <int TYPE>
; __device__ __forceinline__ void attn_mfma_unit2(const AttnCtx& A, unsigned char* ws, LAS unsigned char* lds, int tid, const AUnit& u) {
;     ...
;         for (int ti = 0; ti < nt; ++ti) {
;             if (ti + 1 < nt) A2_DMA(ti + 1, snxt);
;             if (actP) { A2_SETVC(sprv); A2_FSM_PV(sA0, sA1, 0); }
;             actP = A2_ACTIVE(ti);
;             if (actP) { A2_SETKC(scur); A2_QK(sA0, sA1, ti, 0); A2_PSM(sA0, sA1); }
.LBB0_2818:
	s_cmp_gt_u32 s49, 3
	s_cselect_b64 s[12:13], -1, 0
	s_cmp_lt_u32 s49, 4
	s_cselect_b64 s[8:9], -1, 0
	s_add_i32 s49, s15, s47
	s_cmp_ge_i32 s49, s28
	s_cselect_b64 s[50:51], -1, 0
	s_cmp_lt_i32 s49, s43
	s_cselect_b64 s[52:53], -1, 0
	s_and_b64 s[50:51], s[50:51], s[52:53]
	s_or_b64 s[8:9], s[8:9], s[50:51]
	s_andn2_b64 vcc, exec, s[8:9]
	s_cbranch_vccnz .LBB0_2891
	v_add_u32_e32 v0, s44, v202
	ds_read_b128 v[2:5], v0
	ds_read_b128 v[112:115], v0 offset:8192
	v_add_u32_e32 v0, s44, v203
	ds_read_b128 v[116:119], v0
	ds_read_b128 v[120:123], v0 offset:8192
	v_add_u32_e32 v0, s44, v204
	ds_read_b128 v[124:127], v0
	ds_read_b128 v[128:131], v0 offset:8192
	v_add_u32_e32 v0, s44, v205
	ds_read_b128 v[132:135], v0
	ds_read_b128 v[136:139], v0 offset:8192
	v_xor_b32_e32 v80, 0x80000000, v210
	v_mov_b32_e32 v81, v80
	v_mov_b32_e32 v82, v80
	v_mov_b32_e32 v83, v80
	v_mov_b32_e32 v84, v80
	v_mov_b32_e32 v85, v80
	v_mov_b32_e32 v86, v80
	v_mov_b32_e32 v87, v80
	v_mov_b32_e32 v88, v80
	v_mov_b32_e32 v89, v80
	v_mov_b32_e32 v90, v80
	v_mov_b32_e32 v91, v80
	v_mov_b32_e32 v92, v80
	v_mov_b32_e32 v93, v80
	v_mov_b32_e32 v94, v80
	v_mov_b32_e32 v95, v80
	s_andn2_b64 vcc, exec, s[12:13]
	v_add_u32_e32 v0, s44, v206
	s_waitcnt lgkmcnt(7)
	v_mfma_f32_32x32x16_bf16 v[96:111], v[2:5], v[144:147], v[80:95]
	ds_read_b128 v[2:5], v0
	v_add_u32_e32 v0, s44, v207
	s_waitcnt lgkmcnt(6)
	v_mfma_f32_32x32x16_bf16 v[96:111], v[116:119], v[148:151], v[96:111]
	ds_read_b128 v[116:119], v0
	v_add_u32_e32 v0, s44, v206
	v_mfma_f32_32x32x16_bf16 v[80:95], v[112:115], v[144:147], v[80:95]
	ds_read_b128 v[112:115], v0 offset:8192
	v_add_u32_e32 v0, s44, v207
	s_waitcnt lgkmcnt(7)
	v_mfma_f32_32x32x16_bf16 v[80:95], v[120:123], v[148:151], v[80:95]
	ds_read_b128 v[120:123], v0 offset:8192
	v_add_u32_e32 v0, s44, v208
	s_waitcnt lgkmcnt(7)
	v_mfma_f32_32x32x16_bf16 v[96:111], v[124:127], v[152:155], v[96:111]
	ds_read_b128 v[124:127], v0
	v_add_u32_e32 v0, s44, v209
	s_waitcnt lgkmcnt(6)
	v_mfma_f32_32x32x16_bf16 v[96:111], v[132:135], v[156:159], v[96:111]
	ds_read_b128 v[132:135], v0
	v_add_u32_e32 v0, s44, v208
	v_mfma_f32_32x32x16_bf16 v[80:95], v[128:131], v[152:155], v[80:95]
	ds_read_b128 v[128:131], v0 offset:8192
	v_add_u32_e32 v0, s44, v209
	s_waitcnt lgkmcnt(7)
	v_mfma_f32_32x32x16_bf16 v[80:95], v[136:139], v[156:159], v[80:95]
	ds_read_b128 v[136:139], v0 offset:8192
	s_waitcnt lgkmcnt(7)
	v_mfma_f32_32x32x16_bf16 v[96:111], v[2:5], v[160:163], v[96:111]
	s_waitcnt lgkmcnt(6)
	v_mfma_f32_32x32x16_bf16 v[96:111], v[116:119], v[164:167], v[96:111]
	s_waitcnt lgkmcnt(5)
	v_mfma_f32_32x32x16_bf16 v[80:95], v[112:115], v[160:163], v[80:95]
	s_waitcnt lgkmcnt(4)
	v_mfma_f32_32x32x16_bf16 v[80:95], v[120:123], v[164:167], v[80:95]
	s_waitcnt lgkmcnt(3)
	v_mfma_f32_32x32x16_bf16 v[96:111], v[124:127], v[168:171], v[96:111]
	s_waitcnt lgkmcnt(2)
	v_mfma_f32_32x32x16_bf16 v[96:111], v[132:135], v[172:175], v[96:111]
	s_waitcnt lgkmcnt(1)
	v_mfma_f32_32x32x16_bf16 v[80:95], v[128:131], v[168:171], v[80:95]
	s_waitcnt lgkmcnt(0)
	v_mfma_f32_32x32x16_bf16 v[80:95], v[136:139], v[172:175], v[80:95]
	s_nop 1
	s_cbranch_vccnz .LBB0_2885
	v_lshlrev_b32_e32 v0, 2, v197
	v_mov_b32_e32 v5, 0xf149f2ca
	v_add_u32_e32 v0, s46, v0
	ds_read_b32 v128, v0
	ds_read_b32 v129, v0 offset:4
	ds_read_b32 v130, v0 offset:8
	ds_read_b32 v131, v0 offset:12
	ds_read_b32 v132, v0 offset:16
	ds_read_b32 v133, v0 offset:20
	ds_read_b32 v134, v0 offset:24
	ds_read_b32 v135, v0 offset:28
	ds_read_b32 v136, v0 offset:64
	ds_read_b32 v137, v0 offset:68
	ds_read_b32 v138, v0 offset:72
	ds_read_b32 v139, v0 offset:76
	ds_read_b32 v140, v0 offset:80
	ds_read_b32 v141, v0 offset:84
	ds_read_b32 v142, v0 offset:88
	ds_read_b32 v143, v0 offset:92
	ds_read_b32 v112, v0 offset:128
	ds_read_b32 v113, v0 offset:132
	ds_read_b32 v114, v0 offset:136
	ds_read_b32 v115, v0 offset:140
	ds_read_b32 v116, v0 offset:144
	ds_read_b32 v117, v0 offset:148
	ds_read_b32 v118, v0 offset:152
	ds_read_b32 v119, v0 offset:156
	ds_read_b32 v120, v0 offset:192
	ds_read_b32 v121, v0 offset:196
	ds_read_b32 v122, v0 offset:200
	ds_read_b32 v123, v0 offset:204
	ds_read_b32 v124, v0 offset:208
	ds_read_b32 v125, v0 offset:212
	ds_read_b32 v126, v0 offset:216
	ds_read_b32 v127, v0 offset:220
	s_waitcnt lgkmcnt(15)
	v_add_u32_e32 v3, 15, v196
	v_cmp_gt_u32_e32 vcc, 16, v3
	v_add_f32_e32 v96, v96, v128
	v_add_u32_e32 v4, 14, v196
	v_cndmask_b32_e32 v96, v5, v96, vcc
	v_cmp_gt_u32_e32 vcc, 16, v4
	v_add_f32_e32 v97, v97, v129
	v_add_u32_e32 v3, 13, v196
	v_cndmask_b32_e32 v97, v5, v97, vcc
	v_cmp_gt_u32_e32 vcc, 16, v3
	v_add_f32_e32 v98, v98, v130
	v_add_u32_e32 v4, 12, v196
	v_cndmask_b32_e32 v98, v5, v98, vcc
	v_cmp_gt_u32_e32 vcc, 16, v4
	v_add_f32_e32 v99, v99, v131
	v_add_u32_e32 v3, 11, v196
	v_cndmask_b32_e32 v99, v5, v99, vcc
	v_cmp_gt_u32_e32 vcc, 16, v3
	v_add_f32_e32 v100, v100, v132
	v_add_u32_e32 v4, 10, v196
	v_cndmask_b32_e32 v100, v5, v100, vcc
	v_cmp_gt_u32_e32 vcc, 16, v4
	v_add_f32_e32 v101, v101, v133
	v_add_u32_e32 v3, 9, v196
	v_cndmask_b32_e32 v101, v5, v101, vcc
	v_cmp_gt_u32_e32 vcc, 16, v3
	v_add_f32_e32 v102, v102, v134
	v_add_u32_e32 v4, 8, v196
	v_cndmask_b32_e32 v102, v5, v102, vcc
	v_cmp_gt_u32_e32 vcc, 16, v4
	v_add_f32_e32 v103, v103, v135
	v_add_u32_e32 v3, -1, v196
	v_cndmask_b32_e32 v103, v5, v103, vcc
	v_cmp_gt_u32_e32 vcc, 16, v3
	v_add_f32_e32 v104, v104, v136
	v_add_u32_e32 v4, -2, v196
	v_cndmask_b32_e32 v104, v5, v104, vcc
	v_cmp_gt_u32_e32 vcc, 16, v4
	v_add_f32_e32 v105, v105, v137
	v_add_u32_e32 v3, -3, v196
	v_cndmask_b32_e32 v105, v5, v105, vcc
	v_cmp_gt_u32_e32 vcc, 16, v3
	v_add_f32_e32 v106, v106, v138
	v_add_u32_e32 v4, -4, v196
	v_cndmask_b32_e32 v106, v5, v106, vcc
	v_cmp_gt_u32_e32 vcc, 16, v4
	v_add_f32_e32 v107, v107, v139
	v_add_u32_e32 v3, -5, v196
	v_cndmask_b32_e32 v107, v5, v107, vcc
	v_cmp_gt_u32_e32 vcc, 16, v3
	v_add_f32_e32 v108, v108, v140
	v_add_u32_e32 v4, -6, v196
	v_cndmask_b32_e32 v108, v5, v108, vcc
	v_cmp_gt_u32_e32 vcc, 16, v4
	v_add_f32_e32 v109, v109, v141
	v_add_u32_e32 v3, -7, v196
	v_cndmask_b32_e32 v109, v5, v109, vcc
	v_cmp_gt_u32_e32 vcc, 16, v3
	v_add_f32_e32 v110, v110, v142
	v_add_u32_e32 v4, -8, v196
	v_cndmask_b32_e32 v110, v5, v110, vcc
	v_cmp_gt_u32_e32 vcc, 16, v4
	v_add_f32_e32 v111, v111, v143
	v_add_u32_e32 v3, 0xffffffef, v196
	v_cndmask_b32_e32 v111, v5, v111, vcc
	s_waitcnt lgkmcnt(0)
	v_cmp_gt_u32_e32 vcc, 16, v3
	v_add_f32_e32 v80, v80, v112
	v_add_u32_e32 v4, 0xffffffee, v196
	v_cndmask_b32_e32 v80, v5, v80, vcc
	v_cmp_gt_u32_e32 vcc, 16, v4
	v_add_f32_e32 v81, v81, v113
	v_add_u32_e32 v3, 0xffffffed, v196
	v_cndmask_b32_e32 v81, v5, v81, vcc
	v_cmp_gt_u32_e32 vcc, 16, v3
	v_add_f32_e32 v82, v82, v114
	v_add_u32_e32 v4, 0xffffffec, v196
	v_cndmask_b32_e32 v82, v5, v82, vcc
	v_cmp_gt_u32_e32 vcc, 16, v4
	v_add_f32_e32 v83, v83, v115
	v_add_u32_e32 v3, 0xffffffeb, v196
	v_cndmask_b32_e32 v83, v5, v83, vcc
	v_cmp_gt_u32_e32 vcc, 16, v3
	v_add_f32_e32 v84, v84, v116
	v_add_u32_e32 v4, 0xffffffea, v196
	v_cndmask_b32_e32 v84, v5, v84, vcc
	v_cmp_gt_u32_e32 vcc, 16, v4
	v_add_f32_e32 v85, v85, v117
	v_add_u32_e32 v3, 0xffffffe9, v196
	v_cndmask_b32_e32 v85, v5, v85, vcc
	v_cmp_gt_u32_e32 vcc, 16, v3
	v_add_f32_e32 v86, v86, v118
	v_add_u32_e32 v4, 0xffffffe8, v196
	v_cndmask_b32_e32 v86, v5, v86, vcc
	v_cmp_gt_u32_e32 vcc, 16, v4
	v_add_f32_e32 v87, v87, v119
	v_add_u32_e32 v3, 0xffffffdf, v196
	v_cndmask_b32_e32 v87, v5, v87, vcc
	v_cmp_gt_u32_e32 vcc, 16, v3
	v_add_f32_e32 v88, v88, v120
	v_add_u32_e32 v4, 0xffffffde, v196
	v_cndmask_b32_e32 v88, v5, v88, vcc
	v_cmp_gt_u32_e32 vcc, 16, v4
	v_add_f32_e32 v89, v89, v121
	v_add_u32_e32 v3, 0xffffffdd, v196
	v_cndmask_b32_e32 v89, v5, v89, vcc
	v_cmp_gt_u32_e32 vcc, 16, v3
	v_add_f32_e32 v90, v90, v122
	v_add_u32_e32 v4, 0xffffffdc, v196
	v_cndmask_b32_e32 v90, v5, v90, vcc
	v_cmp_gt_u32_e32 vcc, 16, v4
	v_add_f32_e32 v91, v91, v123
	v_add_u32_e32 v3, 0xffffffdb, v196
	v_cndmask_b32_e32 v91, v5, v91, vcc
	v_cmp_gt_u32_e32 vcc, 16, v3
	v_add_f32_e32 v92, v92, v124
	v_add_u32_e32 v4, 0xffffffda, v196
	v_cndmask_b32_e32 v92, v5, v92, vcc
	v_cmp_gt_u32_e32 vcc, 16, v4
	v_add_f32_e32 v93, v93, v125
	v_add_u32_e32 v3, 0xffffffd9, v196
	v_cndmask_b32_e32 v93, v5, v93, vcc
	v_cmp_gt_u32_e32 vcc, 16, v3
	v_add_f32_e32 v94, v94, v126
	v_add_u32_e32 v4, 0xffffffd8, v196
	v_cndmask_b32_e32 v94, v5, v94, vcc
	v_cmp_gt_u32_e32 vcc, 16, v4
	v_add_f32_e32 v95, v95, v127
	s_nop 0
	v_cndmask_b32_e32 v95, v5, v95, vcc
